# P5: accumulator zeroing (128 v_mov per tile) removed on non-first tiles; first-touch MFMAs of the peeled iteration take C=0
# speedup vs baseline: 1.0068x; 1.0038x over previous
;     __device__ __forceinline__ const char* a(const Unit& u) const { return (const char*)A + (size_t)u.pm * 2 * hA(); }
;     __device__ __forceinline__ const char* b(const Unit& u) const { return (const char*)Bt + (size_t)u.pn * 2 * hB() + (size_t)(u.pm >> gshift) * goff; }
;     __device__ __forceinline__ const char* a(const Unit& u) const { return (const char*)A + (size_t)u.pm * 2 * hA(); }
;     __device__ __forceinline__ const char* b(const Unit& u) const { return (const char*)Bt + (size_t)((u.pn >> 4) * 4096 + (u.pn & 15) * 16) * 1024 * 2 + (size_t)(u.pm >> 1) * 512; }
;     __device__ __forceinline__ const char* a(const Unit&) const { return (const char*)A; }
;     __device__ __forceinline__ const char* b(const Unit& u) const { return (const char*)Bt + ((size_t)(((u.pm >> 4) * 1024 + u.pn * 256) * 16 + (u.pm & 15)) * 512) * 2; }
;     __device__ __forceinline__ bool next(int i, Unit& o) const { if (i) return false; o = u; return true; }
;     ...
;         const bool has_next = S.next(ui + 1, nxt);
;         const char* nA = has_next ? g.a(nxt) : cA;
;         const char* nB = has_next ? g.b(nxt) : cB;
.LBB0_715:
	s_ashr_i32 s37, s36, 31
	s_lshl_b64 s[22:23], s[36:37], 20
	s_add_u32 s42, s30, s22
	s_addc_u32 s43, s31, s23
	s_and_b64 s[22:23], s[40:41], exec
	s_cselect_b32 s37, s43, s47
	s_cselect_b32 vcc_lo, s42, s46
	s_ashr_i32 s21, s20, 31
	s_lshl_b64 s[22:23], s[20:21], 20
	s_add_u32 s44, s64, s22
	s_addc_u32 s45, s65, s23
	s_and_b64 s[22:23], s[40:41], exec
	s_cselect_b32 s21, s45, s27
	s_cselect_b32 s86, s44, s26
	s_add_u32 s87, s26, 0x100
	s_addc_u32 s88, s27, 0
	s_mov_b32 s89, -2
	s_cmp_lt_u32 s73, 2
	s_cbranch_scc1 mk_zero_p5
	s_add_u32 s80, s46, 0x100
	s_addc_u32 s81, s47, 0
	s_cmp_eq_u32 s89, 28
	s_cselect_b32 s28, vcc_lo, s80
	s_cselect_b32 s29, s37, s81
	s_cselect_b32 s23, s21, s88
	s_cselect_b32 s22, s86, s87
	s_add_u32 s26, s28, 0x80
	s_addc_u32 s27, s29, 0
	s_add_u32 s66, s22, 0x80
	s_addc_u32 s67, s23, 0
	s_add_u32 s90, s46, 0x80080
	s_addc_u32 s91, s47, 0
	s_add_u32 s52, s28, 0x80000
	s_addc_u32 s53, s29, 0
	s_add_u32 s56, s22, 0x80000
	s_addc_u32 s57, s23, 0
	s_add_u32 s46, s22, 0x80080
	s_addc_u32 s47, s23, 0
	s_add_i32 s92, 0, 0x10000
	v_add_u32_e32 v133, s92, v129
	s_add_i32 s93, 0, 0x14000
	ds_read_b128 v[134:137], v133
	ds_read_b128 v[138:141], v133 offset:1024
	ds_read_b128 v[142:145], v133 offset:2048
	ds_read_b128 v[146:149], v133 offset:3072
	v_add_u32_e32 v133, s93, v129
	ds_read_b128 v[150:153], v133
	ds_read_b128 v[154:157], v133 offset:1024
	ds_read_b128 v[158:161], v133 offset:2048
	ds_read_b128 v[162:165], v133 offset:3072
	s_add_i32 m0, s0, 0xc000
	ds_read_b128 v[166:169], v131
	ds_read_b128 v[170:173], v131 offset:1024
	ds_read_b128 v[174:177], v131 offset:2048
	ds_read_b128 v[178:181], v131 offset:3072
	ds_read_b128 v[182:185], v131 offset:4096
	ds_read_b128 v[186:189], v131 offset:5120
	ds_read_b128 v[202:205], v131 offset:6144
	ds_read_b128 v[206:209], v131 offset:7168
	global_load_lds_dwordx4 v128, s[90:91]
	s_add_i32 m0, s0, 0xe000
	s_nop 0
	global_load_lds_dwordx4 v130, s[90:91]
	s_waitcnt vmcnt(32)
	s_waitcnt lgkmcnt(0)
	s_barrier
	s_setprio 1
	s_waitcnt lgkmcnt(0)
	v_mfma_f32_16x16x32_bf16 v[124:127], v[134:137], v[166:169], 0
	v_mfma_f32_16x16x32_bf16 v[120:123], v[142:145], v[166:169], 0
	v_mfma_f32_16x16x32_bf16 v[108:111], v[134:137], v[174:177], 0
	v_mfma_f32_16x16x32_bf16 v[104:107], v[142:145], v[174:177], 0
	v_mfma_f32_16x16x32_bf16 v[92:95], v[134:137], v[182:185], 0
	v_mfma_f32_16x16x32_bf16 v[88:91], v[142:145], v[182:185], 0
	v_mfma_f32_16x16x32_bf16 v[76:79], v[134:137], v[202:205], 0
	v_mfma_f32_16x16x32_bf16 v[72:75], v[142:145], v[202:205], 0
	v_mfma_f32_16x16x32_bf16 v[124:127], v[138:141], v[170:173], v[124:127]
	v_mfma_f32_16x16x32_bf16 v[120:123], v[146:149], v[170:173], v[120:123]
	v_mfma_f32_16x16x32_bf16 v[108:111], v[138:141], v[178:181], v[108:111]
	v_mfma_f32_16x16x32_bf16 v[104:107], v[146:149], v[178:181], v[104:107]
	v_mfma_f32_16x16x32_bf16 v[92:95], v[138:141], v[186:189], v[92:95]
	v_mfma_f32_16x16x32_bf16 v[88:91], v[146:149], v[186:189], v[88:91]
	v_mfma_f32_16x16x32_bf16 v[76:79], v[138:141], v[206:209], v[76:79]
	v_mfma_f32_16x16x32_bf16 v[72:75], v[146:149], v[206:209], v[72:75]
	s_setprio 0
	s_setprio 1
	v_mfma_f32_16x16x32_bf16 v[116:119], v[150:153], v[166:169], 0
	v_mfma_f32_16x16x32_bf16 v[112:115], v[158:161], v[166:169], 0
	v_mfma_f32_16x16x32_bf16 v[100:103], v[150:153], v[174:177], 0
	v_mfma_f32_16x16x32_bf16 v[96:99], v[158:161], v[174:177], 0
	v_mfma_f32_16x16x32_bf16 v[84:87], v[150:153], v[182:185], 0
	v_mfma_f32_16x16x32_bf16 v[80:83], v[158:161], v[182:185], 0
	v_mfma_f32_16x16x32_bf16 v[68:71], v[150:153], v[202:205], 0
	v_mfma_f32_16x16x32_bf16 v[64:67], v[158:161], v[202:205], 0
	v_mfma_f32_16x16x32_bf16 v[116:119], v[154:157], v[170:173], v[116:119]
	v_mfma_f32_16x16x32_bf16 v[112:115], v[162:165], v[170:173], v[112:115]
	v_mfma_f32_16x16x32_bf16 v[100:103], v[154:157], v[178:181], v[100:103]
	v_mfma_f32_16x16x32_bf16 v[96:99], v[162:165], v[178:181], v[96:99]
	v_mfma_f32_16x16x32_bf16 v[84:87], v[154:157], v[186:189], v[84:87]
	v_mfma_f32_16x16x32_bf16 v[80:83], v[162:165], v[186:189], v[80:83]
	v_mfma_f32_16x16x32_bf16 v[68:71], v[154:157], v[206:209], v[68:71]
	v_mfma_f32_16x16x32_bf16 v[64:67], v[162:165], v[206:209], v[64:67]
	s_setprio 0
	s_barrier
	s_add_i32 s90, s92, s33
	s_mov_b32 m0, s90
	ds_read_b128 v[166:169], v131 offset:16384
	ds_read_b128 v[170:173], v131 offset:17408
	ds_read_b128 v[174:177], v131 offset:18432
	ds_read_b128 v[178:181], v131 offset:19456
	ds_read_b128 v[182:185], v131 offset:20480
	ds_read_b128 v[186:189], v131 offset:21504
	ds_read_b128 v[202:205], v131 offset:22528
	ds_read_b128 v[206:209], v131 offset:23552
	global_load_lds_dwordx4 v192, s[22:23]
	s_add_i32 m0, s90, 0x2000
	s_nop 0
	global_load_lds_dwordx4 v132, s[22:23]
	s_add_i32 s22, s93, s33
	s_mov_b32 m0, s22
	s_nop 0
	global_load_lds_dwordx4 v192, s[56:57]
	s_add_i32 m0, s22, 0x2000
	s_nop 0
	global_load_lds_dwordx4 v132, s[56:57]
	s_mov_b32 m0, s0
	s_nop 0
	global_load_lds_dwordx4 v128, s[28:29]
	s_mov_b32 m0, s1
	s_nop 0
	global_load_lds_dwordx4 v130, s[28:29]
	s_waitcnt vmcnt(32)
	s_waitcnt lgkmcnt(0)
	s_barrier
	s_setprio 1
	s_waitcnt lgkmcnt(0)
	v_mfma_f32_16x16x32_bf16 v[60:63], v[134:137], v[166:169], 0
	v_mfma_f32_16x16x32_bf16 v[56:59], v[142:145], v[166:169], 0
	v_mfma_f32_16x16x32_bf16 v[44:47], v[134:137], v[174:177], 0
	v_mfma_f32_16x16x32_bf16 v[40:43], v[142:145], v[174:177], 0
	v_mfma_f32_16x16x32_bf16 v[28:31], v[134:137], v[182:185], 0
	v_mfma_f32_16x16x32_bf16 v[24:27], v[142:145], v[182:185], 0
	v_mfma_f32_16x16x32_bf16 v[12:15], v[134:137], v[202:205], 0
	v_mfma_f32_16x16x32_bf16 v[8:11], v[142:145], v[202:205], 0
	v_mfma_f32_16x16x32_bf16 v[60:63], v[138:141], v[170:173], v[60:63]
	v_mfma_f32_16x16x32_bf16 v[56:59], v[146:149], v[170:173], v[56:59]
	v_mfma_f32_16x16x32_bf16 v[44:47], v[138:141], v[178:181], v[44:47]
	v_mfma_f32_16x16x32_bf16 v[40:43], v[146:149], v[178:181], v[40:43]
	v_mfma_f32_16x16x32_bf16 v[28:31], v[138:141], v[186:189], v[28:31]
	v_mfma_f32_16x16x32_bf16 v[24:27], v[146:149], v[186:189], v[24:27]
	v_mfma_f32_16x16x32_bf16 v[12:15], v[138:141], v[206:209], v[12:15]
	v_mfma_f32_16x16x32_bf16 v[8:11], v[146:149], v[206:209], v[8:11]
	s_setprio 0
	s_setprio 1
	v_mfma_f32_16x16x32_bf16 v[52:55], v[150:153], v[166:169], 0
	v_mfma_f32_16x16x32_bf16 v[48:51], v[158:161], v[166:169], 0
	v_mfma_f32_16x16x32_bf16 v[36:39], v[150:153], v[174:177], 0
	v_mfma_f32_16x16x32_bf16 v[32:35], v[158:161], v[174:177], 0
	v_mfma_f32_16x16x32_bf16 v[20:23], v[150:153], v[182:185], 0
	v_mfma_f32_16x16x32_bf16 v[16:19], v[158:161], v[182:185], 0
	v_mfma_f32_16x16x32_bf16 v[4:7], v[150:153], v[202:205], 0
	v_mfma_f32_16x16x32_bf16 v[0:3], v[158:161], v[202:205], 0
	v_mfma_f32_16x16x32_bf16 v[52:55], v[154:157], v[170:173], v[52:55]
	v_mfma_f32_16x16x32_bf16 v[48:51], v[162:165], v[170:173], v[48:51]
	v_mfma_f32_16x16x32_bf16 v[36:39], v[154:157], v[178:181], v[36:39]
	v_mfma_f32_16x16x32_bf16 v[32:35], v[162:165], v[178:181], v[32:35]
	v_mfma_f32_16x16x32_bf16 v[20:23], v[154:157], v[186:189], v[20:23]
	v_mfma_f32_16x16x32_bf16 v[16:19], v[162:165], v[186:189], v[16:19]
	v_mfma_f32_16x16x32_bf16 v[4:7], v[154:157], v[206:209], v[4:7]
	v_mfma_f32_16x16x32_bf16 v[0:3], v[162:165], v[206:209], v[0:3]
	s_setprio 0
	s_barrier
	s_add_i32 s22, 0, 0x18000
	v_add_u32_e32 v133, s22, v129
	s_add_i32 s23, 0, 0x1c000
	ds_read_b128 v[134:137], v133
	ds_read_b128 v[138:141], v133 offset:1024
	ds_read_b128 v[142:145], v133 offset:2048
	ds_read_b128 v[146:149], v133 offset:3072
	v_add_u32_e32 v133, s23, v129
	ds_read_b128 v[150:153], v133
	ds_read_b128 v[154:157], v133 offset:1024
	ds_read_b128 v[158:161], v133 offset:2048
	ds_read_b128 v[162:165], v133 offset:3072
	s_mov_b32 m0, s34
	ds_read_b128 v[166:169], v131 offset:32768
	ds_read_b128 v[170:173], v131 offset:33792
	ds_read_b128 v[174:177], v131 offset:34816
	ds_read_b128 v[178:181], v131 offset:35840
	ds_read_b128 v[182:185], v131 offset:36864
	ds_read_b128 v[186:189], v131 offset:37888
	ds_read_b128 v[202:205], v131 offset:38912
	ds_read_b128 v[206:209], v131 offset:39936
	global_load_lds_dwordx4 v128, s[52:53]
	s_mov_b32 m0, s35
	s_nop 0
	global_load_lds_dwordx4 v130, s[52:53]
	s_waitcnt vmcnt(8)
	s_waitcnt lgkmcnt(0)
	s_barrier
	s_setprio 1
	s_waitcnt lgkmcnt(0)
	v_mfma_f32_16x16x32_bf16 v[124:127], v[134:137], v[166:169], v[124:127]
	v_mfma_f32_16x16x32_bf16 v[120:123], v[142:145], v[166:169], v[120:123]
	v_mfma_f32_16x16x32_bf16 v[108:111], v[134:137], v[174:177], v[108:111]
	v_mfma_f32_16x16x32_bf16 v[104:107], v[142:145], v[174:177], v[104:107]
	v_mfma_f32_16x16x32_bf16 v[92:95], v[134:137], v[182:185], v[92:95]
	v_mfma_f32_16x16x32_bf16 v[88:91], v[142:145], v[182:185], v[88:91]
	v_mfma_f32_16x16x32_bf16 v[76:79], v[134:137], v[202:205], v[76:79]
	v_mfma_f32_16x16x32_bf16 v[72:75], v[142:145], v[202:205], v[72:75]
	v_mfma_f32_16x16x32_bf16 v[124:127], v[138:141], v[170:173], v[124:127]
	v_mfma_f32_16x16x32_bf16 v[120:123], v[146:149], v[170:173], v[120:123]
	v_mfma_f32_16x16x32_bf16 v[108:111], v[138:141], v[178:181], v[108:111]
	v_mfma_f32_16x16x32_bf16 v[104:107], v[146:149], v[178:181], v[104:107]
	v_mfma_f32_16x16x32_bf16 v[92:95], v[138:141], v[186:189], v[92:95]
	v_mfma_f32_16x16x32_bf16 v[88:91], v[146:149], v[186:189], v[88:91]
	v_mfma_f32_16x16x32_bf16 v[76:79], v[138:141], v[206:209], v[76:79]
	v_mfma_f32_16x16x32_bf16 v[72:75], v[146:149], v[206:209], v[72:75]
	s_setprio 0
	s_setprio 1
	v_mfma_f32_16x16x32_bf16 v[116:119], v[150:153], v[166:169], v[116:119]
	v_mfma_f32_16x16x32_bf16 v[112:115], v[158:161], v[166:169], v[112:115]
	v_mfma_f32_16x16x32_bf16 v[100:103], v[150:153], v[174:177], v[100:103]
	v_mfma_f32_16x16x32_bf16 v[96:99], v[158:161], v[174:177], v[96:99]
	v_mfma_f32_16x16x32_bf16 v[84:87], v[150:153], v[182:185], v[84:87]
	v_mfma_f32_16x16x32_bf16 v[80:83], v[158:161], v[182:185], v[80:83]
	v_mfma_f32_16x16x32_bf16 v[68:71], v[150:153], v[202:205], v[68:71]
	v_mfma_f32_16x16x32_bf16 v[64:67], v[158:161], v[202:205], v[64:67]
	v_mfma_f32_16x16x32_bf16 v[116:119], v[154:157], v[170:173], v[116:119]
	v_mfma_f32_16x16x32_bf16 v[112:115], v[162:165], v[170:173], v[112:115]
	v_mfma_f32_16x16x32_bf16 v[100:103], v[154:157], v[178:181], v[100:103]
	v_mfma_f32_16x16x32_bf16 v[96:99], v[162:165], v[178:181], v[96:99]
	v_mfma_f32_16x16x32_bf16 v[84:87], v[154:157], v[186:189], v[84:87]
	v_mfma_f32_16x16x32_bf16 v[80:83], v[162:165], v[186:189], v[80:83]
	v_mfma_f32_16x16x32_bf16 v[68:71], v[154:157], v[206:209], v[68:71]
	v_mfma_f32_16x16x32_bf16 v[64:67], v[162:165], v[206:209], v[64:67]
	s_setprio 0
	s_barrier
;     __device__ __forceinline__ const char* a(const Unit& u) const { return (const char*)A + (size_t)u.pm * 2 * hA(); }
;     __device__ __forceinline__ const char* b(const Unit& u) const { return (const char*)Bt + (size_t)u.pn * 2 * hB() + (size_t)(u.pm >> gshift) * goff; }
;     __device__ __forceinline__ const char* a(const Unit& u) const { return (const char*)A + (size_t)u.pm * 2 * hA(); }
;     __device__ __forceinline__ const char* b(const Unit& u) const { return (const char*)Bt + (size_t)((u.pn >> 4) * 4096 + (u.pn & 15) * 16) * 1024 * 2 + (size_t)(u.pm >> 1) * 512; }
;     __device__ __forceinline__ const char* a(const Unit&) const { return (const char*)A; }
;     __device__ __forceinline__ const char* b(const Unit& u) const { return (const char*)Bt + ((size_t)(((u.pm >> 4) * 1024 + u.pn * 256) * 16 + (u.pm & 15)) * 512) * 2; }
; #define PG8_MMA(ai, bj, At, Bt) do { __builtin_amdgcn_s_setprio(1); _Pragma("unroll") for (int m = 0; m < 4; ++m) _Pragma("unroll") for (int n = 0; n < 2; ++n) _Pragma("unroll") for (int k = 0; k < 2; ++k) \
;         acc[ai][bj][m][n] = __builtin_amdgcn_mfma_f32_16x16x32_bf16(Bt[n][k], At[m][k], acc[ai][bj][m][n], 0, 0, 0); __builtin_amdgcn_s_setprio(0); } while (0)
; #define PG8_MMA8(ai, bj, At, Bt) do { __builtin_amdgcn_s_setprio(1); _Pragma("unroll") for (int m = 0; m < 4; ++m) _Pragma("unroll") for (int n = 0; n < 2; ++n) \
;         acc[ai][bj][m][n] = __builtin_amdgcn_mfma_scale_f32_16x16x128_f8f6f4(PG8_CAT(Bt[n][0], Bt[n][1]), PG8_CAT(At[m][0], At[m][1]), acc[ai][bj][m][n], 0, 0, 0, 0, 0, 0); __builtin_amdgcn_s_setprio(0); } while (0)
;     ...
;     f32x4 acc[2][2][4][2];
; #pragma unroll
;     for (int a = 0; a < 2; ++a)
; #pragma unroll
;         for (int b = 0; b < 2; ++b)
; #pragma unroll
;             for (int m = 0; m < 4; ++m)
; #pragma unroll
;                 for (int n = 0; n < 2; ++n) acc[a][b][m][n] = (f32x4){0.f, 0.f, 0.f, 0.f};
;     ...
;         { const int tmid = (TSW > 0 && TSW < nt) ? TSW : nt;
;           _Pragma("unroll 1") for (int t = 0; t < tmid; t += 2) { PG8_BODY(PG8_MMA) }
;           if constexpr (TSW > 0) { _Pragma("unroll 1") for (int t = tmid; t < nt; t += 2) { PG8_BODY(PG8_MMA8) } } }
	s_add_i32 s22, s22, s33
	s_mov_b32 m0, s22
	ds_read_b128 v[166:169], v131 offset:49152
	ds_read_b128 v[170:173], v131 offset:50176
	ds_read_b128 v[174:177], v131 offset:51200
	ds_read_b128 v[178:181], v131 offset:52224
	ds_read_b128 v[182:185], v131 offset:53248
	ds_read_b128 v[186:189], v131 offset:54272
	ds_read_b128 v[202:205], v131 offset:55296
	ds_read_b128 v[206:209], v131 offset:56320
	global_load_lds_dwordx4 v192, s[66:67]
	s_add_i32 m0, s22, 0x2000
	s_add_i32 s22, s23, s33
	global_load_lds_dwordx4 v132, s[66:67]
	s_mov_b32 m0, s22
	s_nop 0
	global_load_lds_dwordx4 v192, s[46:47]
	s_add_i32 m0, s22, 0x2000
	s_nop 0
	global_load_lds_dwordx4 v132, s[46:47]
	s_mov_b32 m0, s54
	s_nop 0
	global_load_lds_dwordx4 v128, s[26:27]
	s_mov_b32 m0, s55
	s_nop 0
	global_load_lds_dwordx4 v130, s[26:27]
	s_waitcnt vmcnt(8)
	s_waitcnt lgkmcnt(0)
	s_barrier
	s_setprio 1
	s_waitcnt lgkmcnt(0)
	v_mfma_f32_16x16x32_bf16 v[60:63], v[134:137], v[166:169], v[60:63]
	v_mfma_f32_16x16x32_bf16 v[56:59], v[142:145], v[166:169], v[56:59]
	v_mfma_f32_16x16x32_bf16 v[44:47], v[134:137], v[174:177], v[44:47]
	v_mfma_f32_16x16x32_bf16 v[40:43], v[142:145], v[174:177], v[40:43]
	v_mfma_f32_16x16x32_bf16 v[28:31], v[134:137], v[182:185], v[28:31]
	v_mfma_f32_16x16x32_bf16 v[24:27], v[142:145], v[182:185], v[24:27]
	v_mfma_f32_16x16x32_bf16 v[12:15], v[134:137], v[202:205], v[12:15]
	v_mfma_f32_16x16x32_bf16 v[8:11], v[142:145], v[202:205], v[8:11]
	v_mfma_f32_16x16x32_bf16 v[60:63], v[138:141], v[170:173], v[60:63]
	v_mfma_f32_16x16x32_bf16 v[56:59], v[146:149], v[170:173], v[56:59]
	v_mfma_f32_16x16x32_bf16 v[44:47], v[138:141], v[178:181], v[44:47]
	v_mfma_f32_16x16x32_bf16 v[40:43], v[146:149], v[178:181], v[40:43]
	v_mfma_f32_16x16x32_bf16 v[28:31], v[138:141], v[186:189], v[28:31]
	v_mfma_f32_16x16x32_bf16 v[24:27], v[146:149], v[186:189], v[24:27]
	v_mfma_f32_16x16x32_bf16 v[12:15], v[138:141], v[206:209], v[12:15]
	v_mfma_f32_16x16x32_bf16 v[8:11], v[146:149], v[206:209], v[8:11]
	s_setprio 0
	s_setprio 1
	v_mfma_f32_16x16x32_bf16 v[52:55], v[150:153], v[166:169], v[52:55]
	v_mfma_f32_16x16x32_bf16 v[48:51], v[158:161], v[166:169], v[48:51]
	v_mfma_f32_16x16x32_bf16 v[36:39], v[150:153], v[174:177], v[36:39]
	v_mfma_f32_16x16x32_bf16 v[32:35], v[158:161], v[174:177], v[32:35]
	v_mfma_f32_16x16x32_bf16 v[20:23], v[150:153], v[182:185], v[20:23]
	v_mfma_f32_16x16x32_bf16 v[16:19], v[158:161], v[182:185], v[16:19]
	v_mfma_f32_16x16x32_bf16 v[4:7], v[150:153], v[202:205], v[4:7]
	v_mfma_f32_16x16x32_bf16 v[0:3], v[158:161], v[202:205], v[0:3]
	v_mfma_f32_16x16x32_bf16 v[52:55], v[154:157], v[170:173], v[52:55]
	v_mfma_f32_16x16x32_bf16 v[48:51], v[162:165], v[170:173], v[48:51]
	v_mfma_f32_16x16x32_bf16 v[36:39], v[154:157], v[178:181], v[36:39]
	v_mfma_f32_16x16x32_bf16 v[32:35], v[162:165], v[178:181], v[32:35]
	v_mfma_f32_16x16x32_bf16 v[20:23], v[154:157], v[186:189], v[20:23]
	v_mfma_f32_16x16x32_bf16 v[16:19], v[162:165], v[186:189], v[16:19]
	v_mfma_f32_16x16x32_bf16 v[4:7], v[154:157], v[206:209], v[4:7]
	v_mfma_f32_16x16x32_bf16 v[0:3], v[162:165], v[206:209], v[0:3]
	s_setprio 0
	s_barrier
	s_add_i32 s89, s89, 2
	s_add_u32 s87, s87, 0x100
	s_addc_u32 s88, s88, 0
	s_cmp_gt_u32 s89, 29
	s_mov_b64 s[46:47], s[80:81]
	s_branch .LBB0_716
mk_zero_p5:
	v_mov_b32_e32 v0, 0
	v_mov_b32_e32 v1, v0
	v_mov_b32_e32 v2, v0
	v_mov_b32_e32 v3, v0
	v_mov_b32_e32 v4, v0
	v_mov_b32_e32 v5, v0
	v_mov_b32_e32 v6, v0
	v_mov_b32_e32 v7, v0
	v_mov_b32_e32 v16, v0
	v_mov_b32_e32 v17, v0
	v_mov_b32_e32 v18, v0
	v_mov_b32_e32 v19, v0
	v_mov_b32_e32 v20, v0
	v_mov_b32_e32 v21, v0
	v_mov_b32_e32 v22, v0
	v_mov_b32_e32 v23, v0
	v_mov_b32_e32 v32, v0
	v_mov_b32_e32 v33, v0
	v_mov_b32_e32 v34, v0
	v_mov_b32_e32 v35, v0
	v_mov_b32_e32 v36, v0
	v_mov_b32_e32 v37, v0
	v_mov_b32_e32 v38, v0
	v_mov_b32_e32 v39, v0
	v_mov_b32_e32 v48, v0
	v_mov_b32_e32 v49, v0
	v_mov_b32_e32 v50, v0
	v_mov_b32_e32 v51, v0
	v_mov_b32_e32 v52, v0
	v_mov_b32_e32 v53, v0
	v_mov_b32_e32 v54, v0
	v_mov_b32_e32 v55, v0
	v_mov_b32_e32 v8, v0
	v_mov_b32_e32 v9, v0
	v_mov_b32_e32 v10, v0
	v_mov_b32_e32 v11, v0
	v_mov_b32_e32 v12, v0
	v_mov_b32_e32 v13, v0
	v_mov_b32_e32 v14, v0
	v_mov_b32_e32 v15, v0
	v_mov_b32_e32 v24, v0
	v_mov_b32_e32 v25, v0
	v_mov_b32_e32 v26, v0
	v_mov_b32_e32 v27, v0
	v_mov_b32_e32 v28, v0
	v_mov_b32_e32 v29, v0
	v_mov_b32_e32 v30, v0
	v_mov_b32_e32 v31, v0
	v_mov_b32_e32 v40, v0
	v_mov_b32_e32 v41, v0
	v_mov_b32_e32 v42, v0
	v_mov_b32_e32 v43, v0
	v_mov_b32_e32 v44, v0
	v_mov_b32_e32 v45, v0
	v_mov_b32_e32 v46, v0
	v_mov_b32_e32 v47, v0
	v_mov_b32_e32 v56, v0
	v_mov_b32_e32 v57, v0
	v_mov_b32_e32 v58, v0
	v_mov_b32_e32 v59, v0
	v_mov_b32_e32 v60, v0
	v_mov_b32_e32 v61, v0
	v_mov_b32_e32 v62, v0
	v_mov_b32_e32 v63, v0
	v_mov_b32_e32 v64, v0
	v_mov_b32_e32 v65, v0
	v_mov_b32_e32 v66, v0
	v_mov_b32_e32 v67, v0
	v_mov_b32_e32 v68, v0
	v_mov_b32_e32 v69, v0
	v_mov_b32_e32 v70, v0
	v_mov_b32_e32 v71, v0
	v_mov_b32_e32 v80, v0
	v_mov_b32_e32 v81, v0
	v_mov_b32_e32 v82, v0
	v_mov_b32_e32 v83, v0
	v_mov_b32_e32 v84, v0
	v_mov_b32_e32 v85, v0
	v_mov_b32_e32 v86, v0
	v_mov_b32_e32 v87, v0
	v_mov_b32_e32 v96, v0
	v_mov_b32_e32 v97, v0
	v_mov_b32_e32 v98, v0
	v_mov_b32_e32 v99, v0
	v_mov_b32_e32 v100, v0
	v_mov_b32_e32 v101, v0
	v_mov_b32_e32 v102, v0
	v_mov_b32_e32 v103, v0
	v_mov_b32_e32 v112, v0
	v_mov_b32_e32 v113, v0
	v_mov_b32_e32 v114, v0
	v_mov_b32_e32 v115, v0
	v_mov_b32_e32 v116, v0
	v_mov_b32_e32 v117, v0
	v_mov_b32_e32 v118, v0
	v_mov_b32_e32 v119, v0
	v_mov_b32_e32 v72, v0
	v_mov_b32_e32 v73, v0
	v_mov_b32_e32 v74, v0
	v_mov_b32_e32 v75, v0
	v_mov_b32_e32 v76, v0
	v_mov_b32_e32 v77, v0
	v_mov_b32_e32 v78, v0
	v_mov_b32_e32 v79, v0
	v_mov_b32_e32 v88, v0
	v_mov_b32_e32 v89, v0
	v_mov_b32_e32 v90, v0
	v_mov_b32_e32 v91, v0
	v_mov_b32_e32 v92, v0
	v_mov_b32_e32 v93, v0
	v_mov_b32_e32 v94, v0
	v_mov_b32_e32 v95, v0
	v_mov_b32_e32 v104, v0
	v_mov_b32_e32 v105, v0
	v_mov_b32_e32 v106, v0
	v_mov_b32_e32 v107, v0
	v_mov_b32_e32 v108, v0
	v_mov_b32_e32 v109, v0
	v_mov_b32_e32 v110, v0
	v_mov_b32_e32 v111, v0
	v_mov_b32_e32 v120, v0
	v_mov_b32_e32 v121, v0
	v_mov_b32_e32 v122, v0
	v_mov_b32_e32 v123, v0
	v_mov_b32_e32 v124, v0
	v_mov_b32_e32 v125, v0
	v_mov_b32_e32 v126, v0
	v_mov_b32_e32 v127, v0
